# next-layer weight conversion split across phase slacks: transpose items 1024..3787 converted behind mla_up (sp3, own counter), pool-map fold + W_mu/W_out items stay behind w_out
# baseline (speedup 1.0000x reference)
; #define LAS __attribute__((address_space(3)))
; __device__ __forceinline__ int opaque_tid(int wv) { int t = wv * 64 + (int)__builtin_amdgcn_mbcnt_hi(~0u, __builtin_amdgcn_mbcnt_lo(~0u, 0u)); asm volatile("" : "+v"(t)); return t; }
; __device__ __forceinline__ void convert_weights(const Args& a, int l, LAS unsigned char* lds, unsigned* ctr, int wave, int lane, int lo, int hi) {
;     LAS float* scr = (LAS float*)(lds + wave * 16384);
;     unsigned char* wb = a.ws + WS_W;
;     bf16_t* WinT = (bf16_t*)(wb + W_IN); bf16_t* WqT = (bf16_t*)(wb + W_Q); bf16_t* WkvT = (bf16_t*)(wb + W_KV);
;     bf16_t* WpuT = (bf16_t*)(wb + W_PU); bf16_t* WmuT = (bf16_t*)(wb + W_MU); bf16_t* WoT = (bf16_t*)(wb + W_O + (size_t)(l & 1) * 1024 * 1024 * 2);
;     const float* w_in = a.w_in + (size_t)l * 1024 * DIN; const float* w_g = a.pool_wg + (size_t)l * 4 * 128 * 128; const float* w_pu = a.pool_wu + (size_t)l * 512 * 1024;
;     const float* w_qb = a.w_qb + (size_t)l * 768 * 768; const float* w_kvb = a.w_kvb + (size_t)l * 256 * 1024; const float* w_mu = a.mla_wu + (size_t)l * 512 * 1024; const float* w_o = a.w_out + (size_t)l * 1024 * 1024;
;     const float* ngain = a.norm_gain + (size_t)l * DM;
; __global__ void __launch_bounds__(512, 2) trunk_fwd(Args a0) {
;     ...
;             if ((sp == 4 && l + 1 < DEPTH) || (sp == 0 && l == 0)) {
;                 const int tid = opaque_tid(wv), lane = tid & 63, wave = __builtin_amdgcn_readfirstlane(tid >> 6);
;                 const bool nxt = (sp == 4);
;                 convert_weights(a, nxt ? l + 1 : 0, lds, (unsigned*)(ws + WS_CTL) + 8192 + 64 * (nxt ? l + 1 : 5), wave, lane, nxt ? 0 : CW_FIRST, CW_NITEMS);
.LBB0_632:
	v_readlane_b32 s0, v252, 2
	v_readlane_b32 s2, v252, 4
	v_readlane_b32 s1, v252, 3
	s_cmp_ge_u32 s21, 3
	s_cselect_b64 s[4:5], -1, 0
	s_cmp_lt_i32 s2, 16
	s_cselect_b64 s[0:1], -1, 0
	s_and_b64 s[0:1], s[0:1], s[4:5]
	v_readlane_b32 s3, v252, 5
	s_cmp_eq_u32 s21, 0
	v_readlane_b32 s6, v254, 52
	s_cselect_b64 s[2:3], -1, 0
	v_readlane_b32 s7, v254, 53
	s_and_b64 s[2:3], s[6:7], s[2:3]
	s_or_b64 s[0:1], s[0:1], s[2:3]
	s_andn2_b64 vcc, exec, s[0:1]
	v_readlane_b32 s83, v254, 34
	v_readlane_b32 s46, v254, 35
	s_cbranch_vccnz .LBB0_735
	v_readlane_b32 s0, v254, 45
	v_readlane_b32 s1, v254, 46
	s_add_i32 s2, s0, 1
	s_and_b64 s[0:1], s[4:5], exec
	s_cselect_b32 s0, s2, 0
	s_lshl_b32 s1, s2, 6
	s_and_b64 s[2:3], s[4:5], exec
	s_cselect_b32 s2, s1, 0x140
	s_cmp_eq_u32 s21, 3
	s_cselect_b32 s1, 32, 0
	s_add_i32 s2, s2, s1
	s_ashr_i32 s3, s2, 31
	s_lshl_b64 s[2:3], s[2:3], 2
	v_readlane_b32 s24, v254, 41
	v_readlane_b32 s25, v254, 42
	s_add_u32 s1, s24, s2
	s_addc_u32 s3, s25, s3
	s_add_u32 s2, s1, 0x8000
	s_waitcnt vmcnt(0)
	v_mov_b32_e32 v3, v228
	s_addc_u32 s3, s3, 0
	s_and_b64 s[4:5], s[4:5], exec
	v_readfirstlane_b32 s6, v3
	s_cselect_b32 s8, 0, 0xc2c
	s_movk_i32 s100, 0x11cc
	s_mov_b32 s101, 0x7fffffff
	s_cmp_eq_u32 s21, 3
	s_cselect_b32 s8, 0x400, s8
	s_cselect_b32 s100, 0xecc, s100
	s_cmp_eq_u32 s21, 4
	s_cselect_b32 s101, 0x400, s101
	s_lshl_b32 s1, s6, 8
	s_and_b32 s13, s1, 0xffffc000
	s_lshl_b32 s1, s0, 21
	s_add_i32 s30, s13, 0
	s_and_b32 s1, s1, 0x200000
	v_readlane_b32 s4, v255, 0
	s_add_u32 s14, s4, s1
	v_readlane_b32 s1, v255, 1
	s_addc_u32 s15, s1, 0
	s_ashr_i32 s1, s0, 31
	v_readlane_b32 s52, v253, 61
	s_lshl_b64 s[4:5], s[0:1], 18
	v_readlane_b32 s62, v254, 7
	v_readlane_b32 s63, v254, 8
	s_add_u32 s9, s62, s4
	v_readlane_b32 s66, v254, 11
	s_addc_u32 s12, s63, s5
	s_lshl_b64 s[16:17], s[0:1], 21
	v_readlane_b32 s60, v254, 5
	v_readlane_b32 s61, v254, 6
	v_readlane_b32 s64, v254, 9
	v_readlane_b32 s65, v254, 10
	v_readlane_b32 s67, v254, 12
	s_add_u32 s4, s66, s16
	s_addc_u32 s5, s67, s17
	v_readlane_b32 s60, v253, 40
	v_and_b32_e32 v5, 63, v3
	s_lshl_b64 s[6:7], s[0:1], 20
	v_readlane_b32 s66, v253, 46
	v_readlane_b32 s67, v253, 47
	s_add_u32 s6, s66, s6
	v_lshlrev_b32_e32 v23, 3, v5
	v_readlane_b32 s72, v253, 52
	s_addc_u32 s7, s67, s7
	v_and_b32_e32 v0, 56, v23
	v_readlane_b32 s73, v253, 53
	s_add_u32 s16, s72, s16
	v_mul_u32_u24_e32 v8, 0x84, v0
	v_lshlrev_b32_e32 v0, 1, v0
	v_readlane_b32 s74, v253, 54
	s_addc_u32 s17, s73, s17
	s_lshl_b64 s[18:19], s[0:1], 22
	v_bfe_u32 v46, v3, 3, 3
	v_lshl_add_u64 v[6:7], s[14:15], 0, v[0:1]
	v_readlane_b32 s14, v255, 4
	v_readlane_b32 s75, v253, 55
	s_add_u32 s18, s74, s18
	v_lshlrev_b32_e32 v9, 2, v46
	v_readlane_b32 s15, v255, 5
	v_readlane_b32 s40, v255, 14
	v_readlane_b32 s58, v254, 3
	s_addc_u32 s19, s75, s19
	s_lshl_b64 s[22:23], s[0:1], 12
	v_add3_u32 v47, s30, v8, v9
	v_lshl_add_u64 v[8:9], s[14:15], 0, v[0:1]
	v_readlane_b32 s14, v255, 8
	v_readlane_b32 s41, v255, 15
	v_readlane_b32 s59, v254, 4
	s_add_u32 s20, s58, s22
	v_readlane_b32 s15, v255, 9
	v_lshl_add_u64 v[12:13], s[40:41], 0, v[0:1]
	v_readlane_b32 s40, v255, 18
	v_readlane_b32 s62, v253, 42
	s_addc_u32 s21, s59, s23
	v_lshl_add_u64 v[10:11], s[14:15], 0, v[0:1]
	s_lshl_b64 s[14:15], s[0:1], 10
	v_readlane_b32 s41, v255, 19
	v_readlane_b32 s63, v253, 43
	v_and_b32_e32 v17, 31, v3
	v_lshl_add_u64 v[14:15], s[40:41], 0, v[0:1]
	s_add_u32 s40, s62, s14
	s_mul_i32 s34, s0, 0x240000
	v_readlane_b32 s64, v253, 44
	v_bfe_u32 v2, v3, 5, 1
	v_lshlrev_b32_e32 v22, 2, v17
	s_addc_u32 s41, s63, s15
	s_mul_hi_i32 s31, s0, 0x240000
	v_readlane_b32 s65, v253, 45
	v_add_u32_e32 v4, s30, v22
	v_lshl_add_u64 v[20:21], s[48:49], 0, v[0:1]
	v_mul_u32_u24_e32 v0, 0x84, v2
	s_add_u32 s30, s64, s34
	s_mul_hi_i32 s38, s0, 0x1220000
	s_mul_i32 s39, s0, 0x1220000
	s_mul_hi_i32 s1, s0, 0xc00
	s_mulk_i32 s0, 0xc00
	v_or_b32_e32 v0, s13, v0
	s_addc_u32 s31, s65, s31
	v_readlane_b32 s13, v253, 39
	s_add_u32 s0, s13, s0
	v_readlane_b32 s13, v253, 56
	v_and_b32_e32 v52, 24, v23
	v_add3_u32 v53, v0, v22, 0
	v_lshlrev_b32_e32 v22, 2, v2
	v_mov_b32_e32 v23, v1
	s_addc_u32 s1, s13, s1
	v_lshl_add_u64 v[24:25], s[0:1], 0, v[22:23]
	v_readlane_b32 s0, v253, 57
	v_readlane_b32 s1, v253, 58
	s_add_u32 s34, s0, s39
	s_addc_u32 s35, s1, s38
	v_readlane_b32 s0, v253, 59
	v_readlane_b32 s1, v253, 60
	s_add_u32 s0, s0, s22
	v_mul_u32_u24_e32 v0, 0x300, v2
	s_addc_u32 s1, s1, s23
	v_lshlrev_b32_e32 v18, 4, v5
	v_mov_b32_e32 v19, v1
	v_or_b32_e32 v55, v0, v17
	v_mul_u32_u24_e32 v0, 0x1220, v2
	v_lshl_add_u64 v[26:27], s[0:1], 0, v[22:23]
	v_readlane_b32 s0, v254, 40
	v_lshl_add_u64 v[18:19], s[24:25], 0, v[18:19]
	s_mov_b64 s[24:25], 0xa10000
	v_or_b32_e32 v63, v0, v17
	s_add_u32 s13, s0, s39
	v_readlane_b32 s0, v254, 13
	v_cmp_eq_u32_e64 s[36:37], 0, v5
	v_or_b32_e32 v48, 8, v46
	v_or_b32_e32 v49, 16, v46
	v_or_b32_e32 v50, 24, v46
	v_lshl_add_u64 v[18:19], v[18:19], 0, s[24:25]
	v_bfe_u32 v51, v3, 2, 4
	v_mov_b32_e32 v3, v2
	v_lshl_or_b32 v54, v2, 10, v17
	v_add_u32_e32 v56, 0x2a00, v55
	v_or_b32_e32 v57, 0x2400, v55
	v_add_u32_e32 v58, 0x1e00, v55
	v_or_b32_e32 v59, 0x1800, v55
	v_add_u32_e32 v60, 0x1200, v55
	v_or_b32_e32 v61, 0xc00, v55
	v_add_u32_e32 v62, 0x600, v55
	v_add_u32_e32 v64, 0xfdc0, v63
	v_add_u32_e32 v65, 0xd980, v63
	v_add_u32_e32 v23, 0xb540, v63
	v_add_u32_e32 v66, 0x9100, v63
	v_add_u32_e32 v67, 0x6cc0, v63
	v_add_u32_e32 v68, 0x4880, v63
	v_add_u32_e32 v69, 0x2440, v63
	s_addc_u32 s14, s0, s38
	v_readlane_b32 s53, v253, 62
	v_readlane_b32 s54, v253, 63
	v_readlane_b32 s55, v254, 0
	v_readlane_b32 s56, v254, 1
	v_readlane_b32 s57, v254, 2
	v_readlane_b32 s61, v253, 41
	v_readlane_b32 s68, v253, 48
	v_readlane_b32 s69, v253, 49
	v_readlane_b32 s70, v253, 50
	v_readlane_b32 s71, v253, 51
	s_branch .LBB0_636

; __device__ __forceinline__ u32x4 zero4() { unsigned z = 0u; asm volatile("" : "+v"(z)); return (u32x4){z, z, z, z}; }
; __device__ __forceinline__ void convert_weights(const Args& a, int l, LAS unsigned char* lds, unsigned* ctr, int wave, int lane, int lo, int hi) {
;     ...
;         int it = 0; if (lane == 0) it = (int)__hip_atomic_fetch_add(ctr, 1u, __ATOMIC_RELAXED, __HIP_MEMORY_SCOPE_AGENT);
;         it = __builtin_amdgcn_readfirstlane(it) + lo;
;         if (it >= hi) break;
;         int r = it;
;         if (r < I_C) { wcomb_item(w_in, w_g, ngain, WinT, r, lane); continue; } r -= I_C;
;         if (r < I_IN) { const int kb = r / 129, nb = r % 129 + 16, n0 = nb * 32; const int d = (n0 < 2048) ? n0 : (n0 < 2080 ? 4608 : n0 - 32);
;             tr_item(w_in, DIN, kb * 64, n0, WinT, 1024, d, kb * 64, scr, lane, ngain); continue; } r -= I_IN;
;         if (r < I_Z) { u32x4* z = (u32x4*)(WinT + (size_t)4640 * 1024) + (size_t)r * 1024 + lane; const u32x4 zz = zero4();
; #pragma unroll
;             for (int i = 0; i < 16; ++i) z[64 * i] = zz;
;             continue; } r -= I_Z;
;         if (r < I_Q) { const int kb = r / 24, nb = r % 24; tr_item(w_qb, 768, kb * 64, nb * 32, WqT, 768, nb * 32, kb * 64, scr, lane, a.qa_gain + (size_t)l * 768); continue; } r -= I_Q;
;         if (r < I_KV) { const int kb = r / 32, nb = r % 32, h = nb >> 2, q = nb & 3;
;             const int d = (q < 2) ? 256 * (h >> 2) + 128 * q + 32 * (h & 3) : 512 + h * 64 + 32 * (q - 2);
;             tr_item(w_kvb, 1024, kb * 64, nb * 32, WkvT, 256, d, kb * 64, scr, lane, a.kva_gain + (size_t)l * 256); continue; } r -= I_KV;
;         if (r < I_PU) { const int kb = r / 32, nb = r % 32; tr_item(w_pu, 1024, kb * 64, nb * 32, WpuT, 512, nb * 32, kb * 64, scr, lane); continue; } r -= I_PU;
;         if (r < I_MU) { const int kb = r / 32, nb = r % 32; tr_item(w_mu, 1024, kb * 64, nb * 32, WmuT, 512, nb * 32, kb * 64, scr, lane); continue; } r -= I_MU;
;         { const int kb = r / 32, nb = r % 32; tr_item(w_o, 1024, kb * 64, nb * 32, WoT, 1024, nb * 32, kb * 64, scr, lane); }
.LBB0_640:
	s_or_b64 exec, exec, s[0:1]
	v_readfirstlane_b32 s15, v0
	s_add_i32 s38, s15, s8
	s_cmp_ge_i32 s38, s101
	s_cselect_b32 s0, 0xacc, 0
	s_add_i32 s38, s38, s0
	s_cmp_ge_i32 s38, s100
	s_mov_b64 s[0:1], -1
	s_cbranch_scc1 .LBB0_635
	s_cmpk_gt_i32 s38, 0x3ff
	s_cbranch_scc0 .LBB0_731
	s_cmpk_gt_u32 s38, 0xc0f
	s_cbranch_scc0 .LBB0_710
	s_cmpk_gt_u32 s38, 0xc2b
	s_cbranch_scc0 .LBB0_707
	s_cmpk_gt_u32 s38, 0xd4b
	s_cbranch_scc0 .LBB0_686
	s_cmpk_gt_u32 s38, 0xdcb
	s_cbranch_scc0 .LBB0_661
	s_cmpk_gt_u32 s38, 0xecb
	s_cbranch_scc0 .LBB0_656
	s_cmpk_gt_u32 s38, 0xfcb
	s_cbranch_scc0 .LBB0_651
	s_add_i32 s0, s38, 0xfffff034
	s_lshl_b32 s1, s0, 1
	s_lshl_b32 s0, s0, 5
	s_and_b32 s0, s0, 0x3e0
	s_and_b32 s1, s1, 0x7fffffc0
	v_or_b32_e32 v28, s0, v17
	s_mov_b32 s22, 1
	s_mov_b32 s23, s1
	v_mov_b32_e32 v5, v28
	s_mov_b32 s39, 0
	s_mov_b32 s42, 32

; __global__ void __launch_bounds__(512, 2) trunk_fwd(Args a0) {
	.amdhsa_kernel _Z9trunk_fwd4Args
		.amdhsa_group_segment_fixed_size 0
		.amdhsa_private_segment_fixed_size 0
		.amdhsa_kernarg_size 408
		.amdhsa_user_sgpr_count 2
		.amdhsa_user_sgpr_dispatch_ptr 0
		.amdhsa_user_sgpr_queue_ptr 0
		.amdhsa_user_sgpr_kernarg_segment_ptr 1
		.amdhsa_user_sgpr_dispatch_id 0
		.amdhsa_user_sgpr_kernarg_preload_length 0
		.amdhsa_user_sgpr_kernarg_preload_offset 0
		.amdhsa_user_sgpr_private_segment_size 0
		.amdhsa_uses_dynamic_stack 0
		.amdhsa_enable_private_segment 0
		.amdhsa_system_sgpr_workgroup_id_x 1
		.amdhsa_system_sgpr_workgroup_id_y 0
		.amdhsa_system_sgpr_workgroup_id_z 0
		.amdhsa_system_sgpr_workgroup_info 0
		.amdhsa_system_vgpr_workitem_id 2
		.amdhsa_next_free_vgpr 256
		.amdhsa_next_free_sgpr 102
		.amdhsa_accum_offset 256
		.amdhsa_reserve_vcc 1
		.amdhsa_float_round_mode_32 0
		.amdhsa_float_round_mode_16_64 0
		.amdhsa_float_denorm_mode_32 3
		.amdhsa_float_denorm_mode_16_64 3
		.amdhsa_dx10_clamp 1
		.amdhsa_ieee_mode 1
		.amdhsa_fp16_overflow 0
		.amdhsa_tg_split 0
		.amdhsa_exception_fp_ieee_invalid_op 0
		.amdhsa_exception_fp_denorm_src 0
		.amdhsa_exception_fp_ieee_div_zero 0
		.amdhsa_exception_fp_ieee_overflow 0
		.amdhsa_exception_fp_ieee_underflow 0
		.amdhsa_exception_fp_ieee_inexact 0
		.amdhsa_exception_int_div_zero 0
	.end_amdhsa_kernel

; __global__ void __launch_bounds__(512, 2) trunk_fwd(Args a0) {
.Lfunc_end0:
	.size	_Z9trunk_fwd4Args, .Lfunc_end0-_Z9trunk_fwd4Args
	.set _Z9trunk_fwd4Args.num_vgpr, 256
	.set _Z9trunk_fwd4Args.num_agpr, 0
	.set _Z9trunk_fwd4Args.numbered_sgpr, 102
	.set _Z9trunk_fwd4Args.num_named_barrier, 0
	.set _Z9trunk_fwd4Args.private_seg_size, 0
	.set _Z9trunk_fwd4Args.uses_vcc, 1
	.set _Z9trunk_fwd4Args.uses_flat_scratch, 0
	.set _Z9trunk_fwd4Args.has_dyn_sized_stack, 0
	.set _Z9trunk_fwd4Args.has_recursion, 0
	.set _Z9trunk_fwd4Args.has_indirect_call, 0

; __global__ void __launch_bounds__(512, 2) trunk_fwd(Args a0) {
amdhsa.kernels:
  - .agpr_count:     0
    .args:
      - .offset:         0
        .size:           152
        .value_kind:     by_value
      - .offset:         152
        .size:           4
        .value_kind:     hidden_block_count_x
      - .offset:         156
        .size:           4
        .value_kind:     hidden_block_count_y
      - .offset:         160
        .size:           4
        .value_kind:     hidden_block_count_z
      - .offset:         164
        .size:           2
        .value_kind:     hidden_group_size_x
      - .offset:         166
        .size:           2
        .value_kind:     hidden_group_size_y
      - .offset:         168
        .size:           2
        .value_kind:     hidden_group_size_z
      - .offset:         170
        .size:           2
        .value_kind:     hidden_remainder_x
      - .offset:         172
        .size:           2
        .value_kind:     hidden_remainder_y
      - .offset:         174
        .size:           2
        .value_kind:     hidden_remainder_z
      - .offset:         192
        .size:           8
        .value_kind:     hidden_global_offset_x
      - .offset:         200
        .size:           8
        .value_kind:     hidden_global_offset_y
      - .offset:         208
        .size:           8
        .value_kind:     hidden_global_offset_z
      - .offset:         216
        .size:           2
        .value_kind:     hidden_grid_dims
      - .offset:         240
        .size:           8
        .value_kind:     hidden_multigrid_sync_arg
      - .offset:         272
        .size:           4
        .value_kind:     hidden_dynamic_lds_size
    .group_segment_fixed_size: 0
    .kernarg_segment_align: 8
    .kernarg_segment_size: 408
    .language:       OpenCL C
    .language_version:
      - 2
      - 0
    .max_flat_workgroup_size: 512
    .name:           _Z9trunk_fwd4Args
    .private_segment_fixed_size: 0
    .sgpr_count:     108
    .sgpr_spill_count: 235
    .symbol:         _Z9trunk_fwd4Args.kd
    .uniform_work_group_size: 1
    .uses_dynamic_stack: false
    .vgpr_count:     256
    .vgpr_spill_count: 0
    .wavefront_size: 64
